# P3 attention: V block staged in a bank-conflict-free LDS layout; PV fragment reads with immediate offsets issued six MFMAs ahead
# speedup vs baseline: 1.0197x; 1.0037x over previous
.LBB0_824:
	v_lshlrev_b32_e32 v0, 4, v0
	v_and_b32_e32 v0, 0xf0, v0
	s_add_i32 s1, 0, 0x11000
	v_add_u32_e32 v7, 0, v0
	v_add_u32_e32 v0, s1, v0
	s_add_u32 s20, s78, 0x800000
	v_readlane_b32 s1, v254, 34
	s_addc_u32 s21, s79, 0
	s_lshr_b32 s22, s1, 7
	s_movk_i32 s1, 0x110
	v_ashrrev_i32_e32 v3, 5, v1
	v_bfe_u32 v5, v1, 2, 2
	v_lshlrev_b32_e32 v11, 1, v1
	v_lshlrev_b32_e32 v13, 3, v1
	v_cmp_gt_u32_e64 s[4:5], 32, v1
	v_mul_lo_u32 v1, v2, s1
	v_mul_lo_u32 v2, v4, s1
	v_mul_lo_u32 v4, v6, s1
	v_mul_lo_u32 v6, v8, s1
	v_mul_lo_u32 v8, v10, s1
	v_mul_lo_u32 v10, v12, s1
	v_mul_lo_u32 v12, v14, s1
	v_mul_lo_u32 v14, v16, s1
	s_movk_i32 s1, 0x440
	v_lshlrev_b32_e32 v196, 3, v3
	v_lshlrev_b32_e32 v9, 4, v3
	v_lshlrev_b32_e32 v217, 2, v3
	v_and_b32_e32 v11, 32, v11
	v_mul_lo_u32 v3, v3, s1
	v_mul_u32_u24_e32 v5, 0x110, v5
	v_and_b32_e32 v13, 24, v13
	s_add_u32 s2, s78, 0x500000
	v_mul_u32_u24_e32 v15, 0x110, v34
	v_add3_u32 v3, v3, v5, v11
	v_ashrrev_i32_e32 v197, 31, v196
	s_addc_u32 s3, s79, 0
	v_add3_u32 v218, v15, v9, 0
	v_add3_u32 v219, v3, v13, 0
	v_mov_b32_e32 v199, 0
	v_add_u32_e32 v220, v7, v1
	v_add_u32_e32 v221, v0, v1
	v_add_u32_e32 v222, v7, v2
	v_add_u32_e32 v223, v0, v2
	v_add_u32_e32 v224, v7, v4
	v_add_u32_e32 v225, v0, v4
	v_add_u32_e32 v226, v7, v6
	v_add_u32_e32 v227, v0, v6
	v_add_u32_e32 v228, v7, v8
	v_add_u32_e32 v229, v0, v8
	v_add_u32_e32 v230, v7, v10
	v_add_u32_e32 v231, v0, v10
	v_add_u32_e32 v232, v7, v12
	v_add_u32_e32 v233, v0, v12
	v_add_u32_e32 v234, v7, v14
	v_add_u32_e32 v235, v0, v14
	v_lshlrev_b64 v[200:201], 1, v[18:19]
	v_lshlrev_b64 v[202:203], 1, v[20:21]
	v_lshlrev_b64 v[204:205], 1, v[22:23]
	v_lshlrev_b64 v[206:207], 1, v[24:25]
	v_lshlrev_b64 v[208:209], 1, v[26:27]
	v_lshlrev_b64 v[210:211], 1, v[28:29]
	v_lshlrev_b64 v[212:213], 1, v[30:31]
	v_lshlrev_b64 v[214:215], 1, v[32:33]
	v_mbcnt_hi_u32_b32 v236, -1, v193
	v_lshrrev_b32_e32 v0, 6, v192
	v_lshlrev_b32_e32 v0, 10, v0
	v_bfe_u32 v1, v192, 2, 2
	v_lshl_add_u32 v0, v1, 8, v0
	v_bfe_u32 v1, v192, 4, 2
	v_lshl_add_u32 v0, v1, 6, v0
	v_and_b32_e32 v1, 3, v192
	v_lshl_add_u32 v0, v1, 4, v0
	v_add_u32_e32 v221, 0x11000, v0
	v_add_u32_e32 v223, 0x2000, v221
	v_add_u32_e32 v225, 0x4000, v221
	v_add_u32_e32 v227, 0x6000, v221
	v_add_u32_e32 v229, 0x8000, v221
	v_add_u32_e32 v231, 0xa000, v221
	v_add_u32_e32 v233, 0xc000, v221
	v_add_u32_e32 v235, 0xe000, v221
	v_lshrrev_b32_e32 v0, 5, v236
	v_lshlrev_b32_e32 v0, 10, v0
	v_bfe_u32 v1, v236, 2, 2
	v_lshl_add_u32 v0, v1, 6, v0
	v_bfe_u32 v1, v236, 4, 1
	v_lshl_add_u32 v0, v1, 5, v0
	v_and_b32_e32 v1, 3, v236
	v_lshl_add_u32 v219, v1, 3, v0
	s_waitcnt vmcnt(0)
	s_branch .LBB0_827

.LBB0_839:
	s_lshl_b32 s98, s11, 8
	v_add_u32_e32 v241, s98, v219
	v_add_u32_e32 v241, 0x11000, v241
	v_cvt_pk_bf16_f32 v0, v0, v1
	v_cvt_pk_bf16_f32 v1, v2, v3
	v_cvt_pk_bf16_f32 v2, v4, v5
	v_cvt_pk_bf16_f32 v3, v6, v7
	v_cvt_pk_bf16_f32 v4, v8, v9
	v_cvt_pk_bf16_f32 v5, v10, v11
	v_cvt_pk_bf16_f32 v6, v12, v13
	v_cvt_pk_bf16_f32 v7, v14, v15
	v_cvt_pk_bf16_f32 v8, v16, v17
	v_cvt_pk_bf16_f32 v9, v18, v19
	v_cvt_pk_bf16_f32 v10, v20, v21
	v_cvt_pk_bf16_f32 v11, v22, v23
	v_cvt_pk_bf16_f32 v12, v24, v25
	v_cvt_pk_bf16_f32 v13, v26, v27
	v_cvt_pk_bf16_f32 v14, v28, v29
	v_cvt_pk_bf16_f32 v15, v30, v31
	ds_read_b64_tr_b16 v[16:17], v241
	ds_read_b64_tr_b16 v[18:19], v241 offset:2048
	ds_read_b64_tr_b16 v[20:21], v241 offset:256
	ds_read_b64_tr_b16 v[22:23], v241 offset:2304
	ds_read_b64_tr_b16 v[24:25], v241 offset:512
	ds_read_b64_tr_b16 v[26:27], v241 offset:2560
	ds_read_b64_tr_b16 v[28:29], v241 offset:768
	ds_read_b64_tr_b16 v[30:31], v241 offset:2816
	ds_read_b64_tr_b16 v[242:243], v241 offset:4096
	ds_read_b64_tr_b16 v[244:245], v241 offset:6144
	ds_read_b64_tr_b16 v[246:247], v241 offset:4352
	ds_read_b64_tr_b16 v[248:249], v241 offset:6400
	ds_read_b64_tr_b16 v[250:251], v241 offset:4608
	ds_read_b64_tr_b16 v[252:253], v241 offset:6656
	s_waitcnt lgkmcnt(12)
	v_mfma_f32_32x32x16_bf16 v[80:95], v[16:19], v[0:3], v[80:95]
	ds_read_b64_tr_b16 v[16:17], v241 offset:4864
	ds_read_b64_tr_b16 v[18:19], v241 offset:6912
	s_waitcnt lgkmcnt(12)
	v_mfma_f32_32x32x16_bf16 v[64:79], v[20:23], v[0:3], v[64:79]
	ds_read_b64_tr_b16 v[20:21], v241 offset:8192
	ds_read_b64_tr_b16 v[22:23], v241 offset:10240
	s_waitcnt lgkmcnt(12)
	v_mfma_f32_32x32x16_bf16 v[48:63], v[24:27], v[0:3], v[48:63]
	ds_read_b64_tr_b16 v[24:25], v241 offset:8448
	ds_read_b64_tr_b16 v[26:27], v241 offset:10496
	s_waitcnt lgkmcnt(12)
	v_mfma_f32_32x32x16_bf16 v[32:47], v[28:31], v[0:3], v[32:47]
	ds_read_b64_tr_b16 v[28:29], v241 offset:8704
	ds_read_b64_tr_b16 v[30:31], v241 offset:10752
	s_waitcnt lgkmcnt(12)
	v_mfma_f32_32x32x16_bf16 v[80:95], v[242:245], v[4:7], v[80:95]
	ds_read_b64_tr_b16 v[242:243], v241 offset:8960
	ds_read_b64_tr_b16 v[244:245], v241 offset:11008
	s_waitcnt lgkmcnt(12)
	v_mfma_f32_32x32x16_bf16 v[64:79], v[246:249], v[4:7], v[64:79]
	ds_read_b64_tr_b16 v[246:247], v241 offset:12288
	ds_read_b64_tr_b16 v[248:249], v241 offset:14336
	s_waitcnt lgkmcnt(12)
	v_mfma_f32_32x32x16_bf16 v[48:63], v[250:253], v[4:7], v[48:63]
	ds_read_b64_tr_b16 v[250:251], v241 offset:12544
	ds_read_b64_tr_b16 v[252:253], v241 offset:14592
	s_waitcnt lgkmcnt(12)
	v_mfma_f32_32x32x16_bf16 v[32:47], v[16:19], v[4:7], v[32:47]
	ds_read_b64_tr_b16 v[16:17], v241 offset:12800
	ds_read_b64_tr_b16 v[18:19], v241 offset:14848
	s_waitcnt lgkmcnt(12)
	v_mfma_f32_32x32x16_bf16 v[80:95], v[20:23], v[8:11], v[80:95]
	ds_read_b64_tr_b16 v[20:21], v241 offset:13056
	ds_read_b64_tr_b16 v[22:23], v241 offset:15104
	s_waitcnt lgkmcnt(12)
	v_mfma_f32_32x32x16_bf16 v[64:79], v[24:27], v[8:11], v[64:79]
	s_waitcnt lgkmcnt(10)
	v_mfma_f32_32x32x16_bf16 v[48:63], v[28:31], v[8:11], v[48:63]
	s_waitcnt lgkmcnt(8)
	v_mfma_f32_32x32x16_bf16 v[32:47], v[242:245], v[8:11], v[32:47]
	s_waitcnt lgkmcnt(6)
	v_mfma_f32_32x32x16_bf16 v[80:95], v[246:249], v[12:15], v[80:95]
	s_waitcnt lgkmcnt(4)
	v_mfma_f32_32x32x16_bf16 v[64:79], v[250:253], v[12:15], v[64:79]
	s_waitcnt lgkmcnt(2)
	v_mfma_f32_32x32x16_bf16 v[48:63], v[16:19], v[12:15], v[48:63]
	s_waitcnt lgkmcnt(0)
	v_mfma_f32_32x32x16_bf16 v[32:47], v[20:23], v[12:15], v[32:47]
	s_add_i32 s11, s11, 64
	s_addk_i32 s1, 0x4400
	s_cmp_eq_u32 s9, s11
	s_cbranch_scc1 .LBB0_841
	v_mov_b32_e32 v241, v240
	s_branch .LBB0_835
